# bf16-row GEMM norm-tile epilogue: cross-lane reductions batched (2x8 swizzles + 4 max rounds instead of 32 waited swizzles); loop heads at baseline offsets mod 8
# speedup vs baseline: 1.0016x; 1.0016x over previous
.Lmy_b16_norm:
	v_fmamk_f32 v158, v236, 0x3a800000, v207
	v_rsq_f32_e32 v158, v158
	s_nop 0
	v_mul_f32_e32 v158, s100, v158
	v_pk_mul_f32 v[126:127], v[126:127], v[158:159] op_sel_hi:[1,0]
	v_pk_mul_f32 v[128:129], v[128:129], v[158:159] op_sel_hi:[1,0]
	v_pk_mul_f32 v[122:123], v[122:123], v[158:159] op_sel_hi:[1,0]
	v_pk_mul_f32 v[124:125], v[124:125], v[158:159] op_sel_hi:[1,0]
	v_cvt_pk_bf16_f32 v146, v126, v127
	v_cvt_pk_bf16_f32 v147, v128, v129
	v_cvt_pk_bf16_f32 v148, v122, v123
	v_cvt_pk_bf16_f32 v149, v124, v125
	ds_bpermute_b32 v168, v145, v146
	ds_bpermute_b32 v169, v145, v147
	ds_bpermute_b32 v170, v145, v148
	ds_bpermute_b32 v171, v145, v149
	v_pk_mul_f32 v[126:127], v[126:127], v[126:127]
	v_pk_mul_f32 v[128:129], v[128:129], v[128:129]
	v_pk_mul_f32 v[122:123], v[122:123], v[122:123]
	v_pk_mul_f32 v[124:125], v[124:125], v[124:125]
	v_add_f32_e32 v178, v126, v127
	v_add_f32_e32 v161, v128, v129
	v_add_f32_e32 v162, v122, v123
	v_add_f32_e32 v163, v124, v125
	v_add_f32_e32 v178, v178, v161
	v_add_f32_e32 v178, v162, v178
	v_add_f32_e32 v178, v163, v178
	v_pk_mul_f32 v[118:119], v[118:119], v[158:159] op_sel_hi:[1,0]
	v_pk_mul_f32 v[120:121], v[120:121], v[158:159] op_sel_hi:[1,0]
	v_pk_mul_f32 v[114:115], v[114:115], v[158:159] op_sel_hi:[1,0]
	v_pk_mul_f32 v[116:117], v[116:117], v[158:159] op_sel_hi:[1,0]
	v_cvt_pk_bf16_f32 v150, v118, v119
	v_cvt_pk_bf16_f32 v151, v120, v121
	v_cvt_pk_bf16_f32 v152, v114, v115
	v_cvt_pk_bf16_f32 v153, v116, v117
	ds_bpermute_b32 v172, v145, v150
	ds_bpermute_b32 v173, v145, v151
	ds_bpermute_b32 v174, v145, v152
	ds_bpermute_b32 v175, v145, v153
	v_pk_mul_f32 v[118:119], v[118:119], v[118:119]
	v_pk_mul_f32 v[120:121], v[120:121], v[120:121]
	v_pk_mul_f32 v[114:115], v[114:115], v[114:115]
	v_pk_mul_f32 v[116:117], v[116:117], v[116:117]
	v_add_f32_e32 v179, v118, v119
	v_add_f32_e32 v161, v120, v121
	v_add_f32_e32 v162, v114, v115
	v_add_f32_e32 v163, v116, v117
	v_add_f32_e32 v179, v179, v161
	v_add_f32_e32 v179, v162, v179
	v_add_f32_e32 v179, v163, v179
	s_waitcnt lgkmcnt(4)
	global_store_dwordx4 v144, v[168:171], s[10:11] nt
	s_add_u32 s54, s10, s12
	s_addc_u32 s55, s11, 0
	s_add_u32 s80, s28, s12
	s_addc_u32 s81, s29, 0
	v_fmamk_f32 v158, v237, 0x3a800000, v207
	v_rsq_f32_e32 v158, v158
	s_nop 0
	v_mul_f32_e32 v158, s100, v158
	v_pk_mul_f32 v[110:111], v[110:111], v[158:159] op_sel_hi:[1,0]
	v_pk_mul_f32 v[112:113], v[112:113], v[158:159] op_sel_hi:[1,0]
	v_pk_mul_f32 v[106:107], v[106:107], v[158:159] op_sel_hi:[1,0]
	v_pk_mul_f32 v[108:109], v[108:109], v[158:159] op_sel_hi:[1,0]
	v_cvt_pk_bf16_f32 v146, v110, v111
	v_cvt_pk_bf16_f32 v147, v112, v113
	v_cvt_pk_bf16_f32 v148, v106, v107
	v_cvt_pk_bf16_f32 v149, v108, v109
	ds_bpermute_b32 v168, v145, v146
	ds_bpermute_b32 v169, v145, v147
	ds_bpermute_b32 v170, v145, v148
	ds_bpermute_b32 v171, v145, v149
	v_pk_mul_f32 v[110:111], v[110:111], v[110:111]
	v_pk_mul_f32 v[112:113], v[112:113], v[112:113]
	v_pk_mul_f32 v[106:107], v[106:107], v[106:107]
	v_pk_mul_f32 v[108:109], v[108:109], v[108:109]
	v_add_f32_e32 v180, v110, v111
	v_add_f32_e32 v161, v112, v113
	v_add_f32_e32 v162, v106, v107
	v_add_f32_e32 v163, v108, v109
	v_add_f32_e32 v180, v180, v161
	v_add_f32_e32 v180, v162, v180
	v_add_f32_e32 v180, v163, v180
	s_waitcnt lgkmcnt(4)
	global_store_dwordx4 v144, v[172:175], s[28:29] nt
	v_pk_mul_f32 v[102:103], v[102:103], v[158:159] op_sel_hi:[1,0]
	v_pk_mul_f32 v[104:105], v[104:105], v[158:159] op_sel_hi:[1,0]
	v_pk_mul_f32 v[96:97], v[96:97], v[158:159] op_sel_hi:[1,0]
	v_pk_mul_f32 v[98:99], v[98:99], v[158:159] op_sel_hi:[1,0]
	v_cvt_pk_bf16_f32 v150, v102, v103
	v_cvt_pk_bf16_f32 v151, v104, v105
	v_cvt_pk_bf16_f32 v152, v96, v97
	v_cvt_pk_bf16_f32 v153, v98, v99
	ds_bpermute_b32 v172, v145, v150
	ds_bpermute_b32 v173, v145, v151
	ds_bpermute_b32 v174, v145, v152
	ds_bpermute_b32 v175, v145, v153
	v_pk_mul_f32 v[102:103], v[102:103], v[102:103]
	v_pk_mul_f32 v[104:105], v[104:105], v[104:105]
	v_pk_mul_f32 v[96:97], v[96:97], v[96:97]
	v_pk_mul_f32 v[98:99], v[98:99], v[98:99]
	v_add_f32_e32 v181, v102, v103
	v_add_f32_e32 v161, v104, v105
	v_add_f32_e32 v162, v96, v97
	v_add_f32_e32 v163, v98, v99
	v_add_f32_e32 v181, v181, v161
	v_add_f32_e32 v181, v162, v181
	v_add_f32_e32 v181, v163, v181
	s_waitcnt lgkmcnt(4)
	global_store_dwordx4 v144, v[168:171], s[54:55] nt
	s_add_u32 s10, s54, s12
	s_addc_u32 s11, s55, 0
	s_add_u32 s28, s80, s12
	s_addc_u32 s29, s81, 0
	v_fmamk_f32 v158, v238, 0x3a800000, v207
	v_rsq_f32_e32 v158, v158
	s_nop 0
	v_mul_f32_e32 v158, s100, v158
	v_pk_mul_f32 v[92:93], v[92:93], v[158:159] op_sel_hi:[1,0]
	v_pk_mul_f32 v[94:95], v[94:95], v[158:159] op_sel_hi:[1,0]
	v_pk_mul_f32 v[88:89], v[88:89], v[158:159] op_sel_hi:[1,0]
	v_pk_mul_f32 v[90:91], v[90:91], v[158:159] op_sel_hi:[1,0]
	v_cvt_pk_bf16_f32 v146, v92, v93
	v_cvt_pk_bf16_f32 v147, v94, v95
	v_cvt_pk_bf16_f32 v148, v88, v89
	v_cvt_pk_bf16_f32 v149, v90, v91
	ds_bpermute_b32 v168, v145, v146
	ds_bpermute_b32 v169, v145, v147
	ds_bpermute_b32 v170, v145, v148
	ds_bpermute_b32 v171, v145, v149
	v_pk_mul_f32 v[92:93], v[92:93], v[92:93]
	v_pk_mul_f32 v[94:95], v[94:95], v[94:95]
	v_pk_mul_f32 v[88:89], v[88:89], v[88:89]
	v_pk_mul_f32 v[90:91], v[90:91], v[90:91]
	v_add_f32_e32 v182, v92, v93
	v_add_f32_e32 v161, v94, v95
	v_add_f32_e32 v162, v88, v89
	v_add_f32_e32 v163, v90, v91
	v_add_f32_e32 v182, v182, v161
	v_add_f32_e32 v182, v162, v182
	v_add_f32_e32 v182, v163, v182
	s_waitcnt lgkmcnt(4)
	global_store_dwordx4 v144, v[172:175], s[80:81] nt
	v_pk_mul_f32 v[84:85], v[84:85], v[158:159] op_sel_hi:[1,0]
	v_pk_mul_f32 v[86:87], v[86:87], v[158:159] op_sel_hi:[1,0]
	v_pk_mul_f32 v[80:81], v[80:81], v[158:159] op_sel_hi:[1,0]
	v_pk_mul_f32 v[82:83], v[82:83], v[158:159] op_sel_hi:[1,0]
	v_cvt_pk_bf16_f32 v150, v84, v85
	v_cvt_pk_bf16_f32 v151, v86, v87
	v_cvt_pk_bf16_f32 v152, v80, v81
	v_cvt_pk_bf16_f32 v153, v82, v83
	ds_bpermute_b32 v172, v145, v150
	ds_bpermute_b32 v173, v145, v151
	ds_bpermute_b32 v174, v145, v152
	ds_bpermute_b32 v175, v145, v153
	v_pk_mul_f32 v[84:85], v[84:85], v[84:85]
	v_pk_mul_f32 v[86:87], v[86:87], v[86:87]
	v_pk_mul_f32 v[80:81], v[80:81], v[80:81]
	v_pk_mul_f32 v[82:83], v[82:83], v[82:83]
	v_add_f32_e32 v183, v84, v85
	v_add_f32_e32 v161, v86, v87
	v_add_f32_e32 v162, v80, v81
	v_add_f32_e32 v163, v82, v83
	v_add_f32_e32 v183, v183, v161
	v_add_f32_e32 v183, v162, v183
	v_add_f32_e32 v183, v163, v183
	s_waitcnt lgkmcnt(4)
	global_store_dwordx4 v144, v[168:171], s[10:11] nt
	s_add_u32 s54, s10, s12
	s_addc_u32 s55, s11, 0
	s_add_u32 s80, s28, s12
	s_addc_u32 s81, s29, 0
	v_fmamk_f32 v158, v239, 0x3a800000, v207
	v_rsq_f32_e32 v158, v158
	s_nop 0
	v_mul_f32_e32 v158, s100, v158
	v_pk_mul_f32 v[76:77], v[76:77], v[158:159] op_sel_hi:[1,0]
	v_pk_mul_f32 v[78:79], v[78:79], v[158:159] op_sel_hi:[1,0]
	v_pk_mul_f32 v[72:73], v[72:73], v[158:159] op_sel_hi:[1,0]
	v_pk_mul_f32 v[74:75], v[74:75], v[158:159] op_sel_hi:[1,0]
	v_cvt_pk_bf16_f32 v146, v76, v77
	v_cvt_pk_bf16_f32 v147, v78, v79
	v_cvt_pk_bf16_f32 v148, v72, v73
	v_cvt_pk_bf16_f32 v149, v74, v75
	ds_bpermute_b32 v168, v145, v146
	ds_bpermute_b32 v169, v145, v147
	ds_bpermute_b32 v170, v145, v148
	ds_bpermute_b32 v171, v145, v149
	v_pk_mul_f32 v[76:77], v[76:77], v[76:77]
	v_pk_mul_f32 v[78:79], v[78:79], v[78:79]
	v_pk_mul_f32 v[72:73], v[72:73], v[72:73]
	v_pk_mul_f32 v[74:75], v[74:75], v[74:75]
	v_add_f32_e32 v184, v76, v77
	v_add_f32_e32 v161, v78, v79
	v_add_f32_e32 v162, v72, v73
	v_add_f32_e32 v163, v74, v75
	v_add_f32_e32 v184, v184, v161
	v_add_f32_e32 v184, v162, v184
	v_add_f32_e32 v184, v163, v184
	s_waitcnt lgkmcnt(4)
	global_store_dwordx4 v144, v[172:175], s[28:29] nt
	v_pk_mul_f32 v[68:69], v[68:69], v[158:159] op_sel_hi:[1,0]
	v_pk_mul_f32 v[70:71], v[70:71], v[158:159] op_sel_hi:[1,0]
	v_pk_mul_f32 v[64:65], v[64:65], v[158:159] op_sel_hi:[1,0]
	v_pk_mul_f32 v[66:67], v[66:67], v[158:159] op_sel_hi:[1,0]
	v_cvt_pk_bf16_f32 v150, v68, v69
	v_cvt_pk_bf16_f32 v151, v70, v71
	v_cvt_pk_bf16_f32 v152, v64, v65
	v_cvt_pk_bf16_f32 v153, v66, v67
	ds_bpermute_b32 v172, v145, v150
	ds_bpermute_b32 v173, v145, v151
	ds_bpermute_b32 v174, v145, v152
	ds_bpermute_b32 v175, v145, v153
	v_pk_mul_f32 v[68:69], v[68:69], v[68:69]
	v_pk_mul_f32 v[70:71], v[70:71], v[70:71]
	v_pk_mul_f32 v[64:65], v[64:65], v[64:65]
	v_pk_mul_f32 v[66:67], v[66:67], v[66:67]
	v_add_f32_e32 v185, v68, v69
	v_add_f32_e32 v161, v70, v71
	v_add_f32_e32 v162, v64, v65
	v_add_f32_e32 v163, v66, v67
	v_add_f32_e32 v185, v185, v161
	v_add_f32_e32 v185, v162, v185
	v_add_f32_e32 v185, v163, v185
	s_waitcnt lgkmcnt(4)
	global_store_dwordx4 v144, v[168:171], s[54:55] nt
	s_add_u32 s10, s54, s13
	s_addc_u32 s11, s55, 0
	s_add_u32 s28, s80, s13
	s_addc_u32 s29, s81, 0
	v_fmamk_f32 v158, v240, 0x3a800000, v207
	v_rsq_f32_e32 v158, v158
	s_nop 0
	v_mul_f32_e32 v158, s100, v158
	v_pk_mul_f32 v[60:61], v[60:61], v[158:159] op_sel_hi:[1,0]
	v_pk_mul_f32 v[62:63], v[62:63], v[158:159] op_sel_hi:[1,0]
	v_pk_mul_f32 v[56:57], v[56:57], v[158:159] op_sel_hi:[1,0]
	v_pk_mul_f32 v[58:59], v[58:59], v[158:159] op_sel_hi:[1,0]
	v_cvt_pk_bf16_f32 v146, v60, v61
	v_cvt_pk_bf16_f32 v147, v62, v63
	v_cvt_pk_bf16_f32 v148, v56, v57
	v_cvt_pk_bf16_f32 v149, v58, v59
	ds_bpermute_b32 v168, v145, v146
	ds_bpermute_b32 v169, v145, v147
	ds_bpermute_b32 v170, v145, v148
	ds_bpermute_b32 v171, v145, v149
	v_pk_mul_f32 v[60:61], v[60:61], v[60:61]
	v_pk_mul_f32 v[62:63], v[62:63], v[62:63]
	v_pk_mul_f32 v[56:57], v[56:57], v[56:57]
	v_pk_mul_f32 v[58:59], v[58:59], v[58:59]
	v_add_f32_e32 v186, v60, v61
	v_add_f32_e32 v161, v62, v63
	v_add_f32_e32 v162, v56, v57
	v_add_f32_e32 v163, v58, v59
	v_add_f32_e32 v186, v186, v161
	v_add_f32_e32 v186, v162, v186
	v_add_f32_e32 v186, v163, v186
	s_waitcnt lgkmcnt(4)
	global_store_dwordx4 v144, v[172:175], s[80:81] nt
	v_pk_mul_f32 v[52:53], v[52:53], v[158:159] op_sel_hi:[1,0]
	v_pk_mul_f32 v[54:55], v[54:55], v[158:159] op_sel_hi:[1,0]
	v_pk_mul_f32 v[48:49], v[48:49], v[158:159] op_sel_hi:[1,0]
	v_pk_mul_f32 v[50:51], v[50:51], v[158:159] op_sel_hi:[1,0]
	v_cvt_pk_bf16_f32 v150, v52, v53
	v_cvt_pk_bf16_f32 v151, v54, v55
	v_cvt_pk_bf16_f32 v152, v48, v49
	v_cvt_pk_bf16_f32 v153, v50, v51
	ds_bpermute_b32 v172, v145, v150
	ds_bpermute_b32 v173, v145, v151
	ds_bpermute_b32 v174, v145, v152
	ds_bpermute_b32 v175, v145, v153
	v_pk_mul_f32 v[52:53], v[52:53], v[52:53]
	v_pk_mul_f32 v[54:55], v[54:55], v[54:55]
	v_pk_mul_f32 v[48:49], v[48:49], v[48:49]
	v_pk_mul_f32 v[50:51], v[50:51], v[50:51]
	v_add_f32_e32 v187, v52, v53
	v_add_f32_e32 v161, v54, v55
	v_add_f32_e32 v162, v48, v49
	v_add_f32_e32 v163, v50, v51
	v_add_f32_e32 v187, v187, v161
	v_add_f32_e32 v187, v162, v187
	v_add_f32_e32 v187, v163, v187
	s_waitcnt lgkmcnt(4)
	global_store_dwordx4 v144, v[168:171], s[10:11] nt
	s_add_u32 s54, s10, s12
	s_addc_u32 s55, s11, 0
	s_add_u32 s80, s28, s12
	s_addc_u32 s81, s29, 0
	v_fmamk_f32 v158, v244, 0x3a800000, v207
	v_rsq_f32_e32 v158, v158
	s_nop 0
	v_mul_f32_e32 v158, s100, v158
	v_pk_mul_f32 v[44:45], v[44:45], v[158:159] op_sel_hi:[1,0]
	v_pk_mul_f32 v[46:47], v[46:47], v[158:159] op_sel_hi:[1,0]
	v_pk_mul_f32 v[40:41], v[40:41], v[158:159] op_sel_hi:[1,0]
	v_pk_mul_f32 v[42:43], v[42:43], v[158:159] op_sel_hi:[1,0]
	v_cvt_pk_bf16_f32 v146, v44, v45
	v_cvt_pk_bf16_f32 v147, v46, v47
	v_cvt_pk_bf16_f32 v148, v40, v41
	v_cvt_pk_bf16_f32 v149, v42, v43
	ds_bpermute_b32 v168, v145, v146
	ds_bpermute_b32 v169, v145, v147
	ds_bpermute_b32 v170, v145, v148
	ds_bpermute_b32 v171, v145, v149
	v_pk_mul_f32 v[44:45], v[44:45], v[44:45]
	v_pk_mul_f32 v[46:47], v[46:47], v[46:47]
	v_pk_mul_f32 v[40:41], v[40:41], v[40:41]
	v_pk_mul_f32 v[42:43], v[42:43], v[42:43]
	v_add_f32_e32 v188, v44, v45
	v_add_f32_e32 v161, v46, v47
	v_add_f32_e32 v162, v40, v41
	v_add_f32_e32 v163, v42, v43
	v_add_f32_e32 v188, v188, v161
	v_add_f32_e32 v188, v162, v188
	v_add_f32_e32 v188, v163, v188
	s_waitcnt lgkmcnt(4)
	global_store_dwordx4 v144, v[172:175], s[28:29] nt
	v_pk_mul_f32 v[36:37], v[36:37], v[158:159] op_sel_hi:[1,0]
	v_pk_mul_f32 v[38:39], v[38:39], v[158:159] op_sel_hi:[1,0]
	v_pk_mul_f32 v[32:33], v[32:33], v[158:159] op_sel_hi:[1,0]
	v_pk_mul_f32 v[34:35], v[34:35], v[158:159] op_sel_hi:[1,0]
	v_cvt_pk_bf16_f32 v150, v36, v37
	v_cvt_pk_bf16_f32 v151, v38, v39
	v_cvt_pk_bf16_f32 v152, v32, v33
	v_cvt_pk_bf16_f32 v153, v34, v35
	ds_bpermute_b32 v172, v145, v150
	ds_bpermute_b32 v173, v145, v151
	ds_bpermute_b32 v174, v145, v152
	ds_bpermute_b32 v175, v145, v153
	v_pk_mul_f32 v[36:37], v[36:37], v[36:37]
	v_pk_mul_f32 v[38:39], v[38:39], v[38:39]
	v_pk_mul_f32 v[32:33], v[32:33], v[32:33]
	v_pk_mul_f32 v[34:35], v[34:35], v[34:35]
	v_add_f32_e32 v189, v36, v37
	v_add_f32_e32 v161, v38, v39
	v_add_f32_e32 v162, v32, v33
	v_add_f32_e32 v163, v34, v35
	v_add_f32_e32 v189, v189, v161
	v_add_f32_e32 v189, v162, v189
	v_add_f32_e32 v189, v163, v189
	s_waitcnt lgkmcnt(4)
	global_store_dwordx4 v144, v[168:171], s[54:55] nt
	s_add_u32 s10, s54, s12
	s_addc_u32 s11, s55, 0
	s_add_u32 s28, s80, s12
	s_addc_u32 s29, s81, 0
	v_fmamk_f32 v158, v245, 0x3a800000, v207
	v_rsq_f32_e32 v158, v158
	s_nop 0
	v_mul_f32_e32 v158, s100, v158
	v_pk_mul_f32 v[28:29], v[28:29], v[158:159] op_sel_hi:[1,0]
	v_pk_mul_f32 v[30:31], v[30:31], v[158:159] op_sel_hi:[1,0]
	v_pk_mul_f32 v[24:25], v[24:25], v[158:159] op_sel_hi:[1,0]
	v_pk_mul_f32 v[26:27], v[26:27], v[158:159] op_sel_hi:[1,0]
	v_cvt_pk_bf16_f32 v146, v28, v29
	v_cvt_pk_bf16_f32 v147, v30, v31
	v_cvt_pk_bf16_f32 v148, v24, v25
	v_cvt_pk_bf16_f32 v149, v26, v27
	ds_bpermute_b32 v168, v145, v146
	ds_bpermute_b32 v169, v145, v147
	ds_bpermute_b32 v170, v145, v148
	ds_bpermute_b32 v171, v145, v149
	v_pk_mul_f32 v[28:29], v[28:29], v[28:29]
	v_pk_mul_f32 v[30:31], v[30:31], v[30:31]
	v_pk_mul_f32 v[24:25], v[24:25], v[24:25]
	v_pk_mul_f32 v[26:27], v[26:27], v[26:27]
	v_add_f32_e32 v190, v28, v29
	v_add_f32_e32 v161, v30, v31
	v_add_f32_e32 v162, v24, v25
	v_add_f32_e32 v163, v26, v27
	v_add_f32_e32 v190, v190, v161
	v_add_f32_e32 v190, v162, v190
	v_add_f32_e32 v190, v163, v190
	s_waitcnt lgkmcnt(4)
	global_store_dwordx4 v144, v[172:175], s[80:81] nt
	v_pk_mul_f32 v[20:21], v[20:21], v[158:159] op_sel_hi:[1,0]
	v_pk_mul_f32 v[22:23], v[22:23], v[158:159] op_sel_hi:[1,0]
	v_pk_mul_f32 v[16:17], v[16:17], v[158:159] op_sel_hi:[1,0]
	v_pk_mul_f32 v[18:19], v[18:19], v[158:159] op_sel_hi:[1,0]
	v_cvt_pk_bf16_f32 v150, v20, v21
	v_cvt_pk_bf16_f32 v151, v22, v23
	v_cvt_pk_bf16_f32 v152, v16, v17
	v_cvt_pk_bf16_f32 v153, v18, v19
	ds_bpermute_b32 v172, v145, v150
	ds_bpermute_b32 v173, v145, v151
	ds_bpermute_b32 v174, v145, v152
	ds_bpermute_b32 v175, v145, v153
	v_pk_mul_f32 v[20:21], v[20:21], v[20:21]
	v_pk_mul_f32 v[22:23], v[22:23], v[22:23]
	v_pk_mul_f32 v[16:17], v[16:17], v[16:17]
	v_pk_mul_f32 v[18:19], v[18:19], v[18:19]
	v_add_f32_e32 v191, v20, v21
	v_add_f32_e32 v161, v22, v23
	v_add_f32_e32 v162, v16, v17
	v_add_f32_e32 v163, v18, v19
	v_add_f32_e32 v191, v191, v161
	v_add_f32_e32 v191, v162, v191
	v_add_f32_e32 v191, v163, v191
	s_waitcnt lgkmcnt(4)
	global_store_dwordx4 v144, v[168:171], s[10:11] nt
	s_add_u32 s54, s10, s12
	s_addc_u32 s55, s11, 0
	s_add_u32 s80, s28, s12
	s_addc_u32 s81, s29, 0
	v_fmamk_f32 v158, v246, 0x3a800000, v207
	v_rsq_f32_e32 v158, v158
	s_nop 0
	v_mul_f32_e32 v158, s100, v158
	v_pk_mul_f32 v[12:13], v[12:13], v[158:159] op_sel_hi:[1,0]
	v_pk_mul_f32 v[14:15], v[14:15], v[158:159] op_sel_hi:[1,0]
	v_pk_mul_f32 v[8:9], v[8:9], v[158:159] op_sel_hi:[1,0]
	v_pk_mul_f32 v[10:11], v[10:11], v[158:159] op_sel_hi:[1,0]
	v_cvt_pk_bf16_f32 v146, v12, v13
	v_cvt_pk_bf16_f32 v147, v14, v15
	v_cvt_pk_bf16_f32 v148, v8, v9
	v_cvt_pk_bf16_f32 v149, v10, v11
	ds_bpermute_b32 v168, v145, v146
	ds_bpermute_b32 v169, v145, v147
	ds_bpermute_b32 v170, v145, v148
	ds_bpermute_b32 v171, v145, v149
	v_pk_mul_f32 v[12:13], v[12:13], v[12:13]
	v_pk_mul_f32 v[14:15], v[14:15], v[14:15]
	v_pk_mul_f32 v[8:9], v[8:9], v[8:9]
	v_pk_mul_f32 v[10:11], v[10:11], v[10:11]
	v_add_f32_e32 v192, v12, v13
	v_add_f32_e32 v161, v14, v15
	v_add_f32_e32 v162, v8, v9
	v_add_f32_e32 v163, v10, v11
	v_add_f32_e32 v192, v192, v161
	v_add_f32_e32 v192, v162, v192
	v_add_f32_e32 v192, v163, v192
	s_waitcnt lgkmcnt(4)
	global_store_dwordx4 v144, v[172:175], s[28:29] nt
	v_pk_mul_f32 v[4:5], v[4:5], v[158:159] op_sel_hi:[1,0]
	v_pk_mul_f32 v[6:7], v[6:7], v[158:159] op_sel_hi:[1,0]
	v_pk_mul_f32 v[0:1], v[0:1], v[158:159] op_sel_hi:[1,0]
	v_pk_mul_f32 v[2:3], v[2:3], v[158:159] op_sel_hi:[1,0]
	v_cvt_pk_bf16_f32 v150, v4, v5
	v_cvt_pk_bf16_f32 v151, v6, v7
	v_cvt_pk_bf16_f32 v152, v0, v1
	v_cvt_pk_bf16_f32 v153, v2, v3
	ds_bpermute_b32 v172, v145, v150
	ds_bpermute_b32 v173, v145, v151
	ds_bpermute_b32 v174, v145, v152
	ds_bpermute_b32 v175, v145, v153
	v_pk_mul_f32 v[4:5], v[4:5], v[4:5]
	v_pk_mul_f32 v[6:7], v[6:7], v[6:7]
	v_pk_mul_f32 v[0:1], v[0:1], v[0:1]
	v_pk_mul_f32 v[2:3], v[2:3], v[2:3]
	v_add_f32_e32 v193, v4, v5
	v_add_f32_e32 v161, v6, v7
	v_add_f32_e32 v162, v0, v1
	v_add_f32_e32 v163, v2, v3
	v_add_f32_e32 v193, v193, v161
	v_add_f32_e32 v193, v162, v193
	v_add_f32_e32 v193, v163, v193
	s_waitcnt lgkmcnt(4)
	global_store_dwordx4 v144, v[168:171], s[54:55] nt
	s_waitcnt lgkmcnt(0)
	global_store_dwordx4 v144, v[172:175], s[80:81] nt
	ds_swizzle_b32 v194, v178 offset:swizzle(SWAP,16)
	ds_swizzle_b32 v195, v179 offset:swizzle(SWAP,16)
	ds_swizzle_b32 v196, v180 offset:swizzle(SWAP,16)
	ds_swizzle_b32 v197, v181 offset:swizzle(SWAP,16)
	ds_swizzle_b32 v198, v182 offset:swizzle(SWAP,16)
	ds_swizzle_b32 v199, v183 offset:swizzle(SWAP,16)
	ds_swizzle_b32 v200, v184 offset:swizzle(SWAP,16)
	ds_swizzle_b32 v201, v185 offset:swizzle(SWAP,16)
	s_waitcnt lgkmcnt(0)
	v_add_f32_e32 v178, v178, v194
	v_mov_b32_e32 v194, v178
	v_add_f32_e32 v179, v179, v195
	v_mov_b32_e32 v195, v179
	v_add_f32_e32 v180, v180, v196
	v_mov_b32_e32 v196, v180
	v_add_f32_e32 v181, v181, v197
	v_mov_b32_e32 v197, v181
	v_add_f32_e32 v182, v182, v198
	v_mov_b32_e32 v198, v182
	v_add_f32_e32 v183, v183, v199
	v_mov_b32_e32 v199, v183
	v_add_f32_e32 v184, v184, v200
	v_mov_b32_e32 v200, v184
	v_add_f32_e32 v185, v185, v201
	v_mov_b32_e32 v201, v185
	ds_swizzle_b32 v202, v186 offset:swizzle(SWAP,16)
	ds_swizzle_b32 v203, v187 offset:swizzle(SWAP,16)
	ds_swizzle_b32 v204, v188 offset:swizzle(SWAP,16)
	ds_swizzle_b32 v205, v189 offset:swizzle(SWAP,16)
	ds_swizzle_b32 v160, v190 offset:swizzle(SWAP,16)
	ds_swizzle_b32 v161, v191 offset:swizzle(SWAP,16)
	ds_swizzle_b32 v162, v192 offset:swizzle(SWAP,16)
	ds_swizzle_b32 v163, v193 offset:swizzle(SWAP,16)
	s_waitcnt lgkmcnt(0)
	v_add_f32_e32 v186, v186, v202
	v_mov_b32_e32 v202, v186
	v_add_f32_e32 v187, v187, v203
	v_mov_b32_e32 v203, v187
	v_add_f32_e32 v188, v188, v204
	v_mov_b32_e32 v204, v188
	v_add_f32_e32 v189, v189, v205
	v_mov_b32_e32 v205, v189
	v_add_f32_e32 v190, v190, v160
	v_mov_b32_e32 v160, v190
	v_add_f32_e32 v191, v191, v161
	v_mov_b32_e32 v161, v191
	v_add_f32_e32 v192, v192, v162
	v_mov_b32_e32 v162, v192
	v_add_f32_e32 v193, v193, v163
	v_mov_b32_e32 v163, v193
	s_nop 1
	v_permlane32_swap_b32_e32 v178, v194
	v_permlane32_swap_b32_e32 v179, v195
	v_permlane32_swap_b32_e32 v180, v196
	v_permlane32_swap_b32_e32 v181, v197
	v_permlane32_swap_b32_e32 v182, v198
	v_permlane32_swap_b32_e32 v183, v199
	v_permlane32_swap_b32_e32 v184, v200
	v_permlane32_swap_b32_e32 v185, v201
	v_permlane32_swap_b32_e32 v186, v202
	v_permlane32_swap_b32_e32 v187, v203
	v_permlane32_swap_b32_e32 v188, v204
	v_permlane32_swap_b32_e32 v189, v205
	v_permlane32_swap_b32_e32 v190, v160
	v_permlane32_swap_b32_e32 v191, v161
	v_permlane32_swap_b32_e32 v192, v162
	v_permlane32_swap_b32_e32 v193, v163
	v_add_f32_e32 v178, v178, v194
	v_add_f32_e32 v179, v179, v195
	v_add_f32_e32 v180, v180, v196
	v_add_f32_e32 v181, v181, v197
	v_add_f32_e32 v182, v182, v198
	v_add_f32_e32 v183, v183, v199
	v_add_f32_e32 v184, v184, v200
	v_add_f32_e32 v185, v185, v201
	v_add_f32_e32 v186, v186, v202
	v_add_f32_e32 v187, v187, v203
	v_add_f32_e32 v188, v188, v204
	v_add_f32_e32 v189, v189, v205
	v_add_f32_e32 v190, v190, v160
	v_add_f32_e32 v191, v191, v161
	v_add_f32_e32 v192, v192, v162
	v_add_f32_e32 v193, v193, v163
	v_max3_f32 v164, v178, v180, 0
	v_max3_f32 v164, v164, v182, v184
	v_max3_f32 v165, v179, v181, 0
	v_max3_f32 v165, v165, v183, v185
	v_max3_f32 v166, v186, v188, 0
	v_max3_f32 v166, v166, v190, v192
	v_max3_f32 v167, v187, v189, 0
	v_max3_f32 v167, v167, v191, v193
	ds_swizzle_b32 v194, v164 offset:swizzle(SWAP,1)
	ds_swizzle_b32 v195, v165 offset:swizzle(SWAP,1)
	ds_swizzle_b32 v196, v166 offset:swizzle(SWAP,1)
	ds_swizzle_b32 v197, v167 offset:swizzle(SWAP,1)
	s_waitcnt lgkmcnt(0)
	v_max_f32_e32 v164, v164, v194
	v_max_f32_e32 v165, v165, v195
	v_max_f32_e32 v166, v166, v196
	v_max_f32_e32 v167, v167, v197
	ds_swizzle_b32 v194, v164 offset:swizzle(SWAP,2)
	ds_swizzle_b32 v195, v165 offset:swizzle(SWAP,2)
	ds_swizzle_b32 v196, v166 offset:swizzle(SWAP,2)
	ds_swizzle_b32 v197, v167 offset:swizzle(SWAP,2)
	s_waitcnt lgkmcnt(0)
	v_max_f32_e32 v164, v164, v194
	v_max_f32_e32 v165, v165, v195
	v_max_f32_e32 v166, v166, v196
	v_max_f32_e32 v167, v167, v197
	ds_swizzle_b32 v194, v164 offset:swizzle(SWAP,4)
	ds_swizzle_b32 v195, v165 offset:swizzle(SWAP,4)
	ds_swizzle_b32 v196, v166 offset:swizzle(SWAP,4)
	ds_swizzle_b32 v197, v167 offset:swizzle(SWAP,4)
	s_waitcnt lgkmcnt(0)
	v_max_f32_e32 v164, v164, v194
	v_max_f32_e32 v165, v165, v195
	v_max_f32_e32 v166, v166, v196
	v_max_f32_e32 v167, v167, v197
	ds_swizzle_b32 v194, v164 offset:swizzle(SWAP,8)
	ds_swizzle_b32 v195, v165 offset:swizzle(SWAP,8)
	ds_swizzle_b32 v196, v166 offset:swizzle(SWAP,8)
	ds_swizzle_b32 v197, v167 offset:swizzle(SWAP,8)
	s_waitcnt lgkmcnt(0)
	v_max_f32_e32 v164, v164, v194
	v_max_f32_e32 v165, v165, v195
	v_max_f32_e32 v166, v166, v196
	v_max_f32_e32 v167, v167, v197
	s_ashr_i32 s11, s40, 5
	s_lshl_b32 s14, s47, 3
	s_add_i32 s14, s14, s11
	s_lshl_b32 s14, s14, 10
	s_ashr_i32 s15, s33, 6
	s_add_i32 s15, s15, s94
	s_lshl_b32 s15, s15, 6
	s_add_i32 s14, s14, s15
	s_lshl_b32 s15, s40, 1
	s_and_b32 s15, s15, 62
	s_or_b32 s14, s14, s15
	s_lshl_b32 s14, s14, 3
	s_add_u32 s14, s95, s14
	s_addc_u32 s15, s98, 0
	s_and_saveexec_b64 s[12:13], s[6:7]
	s_cbranch_execz .Lmy_b16_noatom
	global_atomic_umax v101, v164, s[14:15]
	global_atomic_umax v101, v165, s[14:15] offset:1024
	global_atomic_umax v101, v166, s[14:15] offset:8
	global_atomic_umax v101, v167, s[14:15] offset:1032
